# weight-conversion in-loop loads: wait deferred to the consumer (next tile-out) with counted vmcnt(18)/(2); uniform 16 loads per job
# speedup vs baseline: 1.0131x; 1.0114x over previous
; __device__ __forceinline__ void prep_load(const KP& p, int job, int tid, float (&v)[8], PrepMeta& m) {
;   int l = job / 5440, j = job % 5440;
;   int mat, nt, kt, K; size_t woff;
;   const float *s0, *s1, *sc; int ldn; float cs;
;   if (j < 1408) { mat = 0; nt = j / 16; kt = j % 16; K = DM; woff = W_GUA; s0 = p.in[7] + (size_t)l * DM * DFF; s1 = p.in[8] + (size_t)l * DM * DFF; sc = p.in[6] + l * DM; ldn = DFF; cs = 1.f; }
;   else if (j < 2112) { j -= 1408; mat = 1; nt = j / 44; kt = j % 44; K = DFF; woff = W_DA; s0 = s1 = p.in[9] + (size_t)l * DFF * DM; sc = nullptr; ldn = DM; cs = 0.5f; }
;   else if (j < 3072) { j -= 2112; mat = 2; nt = j / 16; kt = j % 16; K = DM; woff = W_IN; s0 = s1 = p.in[11] + (size_t)l * DM * 3592; sc = p.in[10] + l * DM; ldn = 3592; cs = 1.f; }
;   else if (j < 3328) { j -= 3072; mat = 3; nt = j / 16; kt = j % 16; K = DM; woff = W_OUT; s0 = s1 = p.in[20] + (size_t)l * DM * DM; sc = nullptr; ldn = DM; cs = 1.f; }
;   else if (j < 4736) { j -= 3328; mat = 0; nt = j / 16; kt = j % 16; K = DM; woff = W_GUB; s0 = p.in[22] + (size_t)l * DM * DFF; s1 = p.in[23] + (size_t)l * DM * DFF; sc = p.in[21] + l * DM; ldn = DFF; cs = 1.f; }
;   else { j -= 4736; mat = 1; nt = j / 44; kt = j % 44; K = DFF; woff = W_DB; s0 = s1 = p.in[24] + (size_t)l * DFF * DM; sc = nullptr; ldn = DM; cs = 0.5f; }
; __device__ void phase_prep(const KP& p, int job_lo, int job_hi, int first_blk) {
;     ...
;   const int total = (p.bid < first_blk) ? 0 : job_hi, stride = p.nblk - first_blk;
;   float va[8], vb[8]; PrepMeta ma, mb;
;   const int j0 = job_lo + (p.bid - first_blk);
;   if (j0 < total) prep_load(p, j0, tid, va, ma);
.Lsub_skip:
	s_mov_b32 s98, 0
	s_mov_b32 s99, 0
	s_mov_b32 s100, 0
	s_mov_b32 s101, 0
	s_and_b64 vcc, exec, s[88:89]
	s_cbranch_vccz .LBB0_220
	s_cmp_le_u32 s33, s95
	s_cbranch_scc1 .LBB0_195
	v_readlane_b32 s0, v255, 42
	s_cmp_ge_i32 s0, s67
	s_cselect_b32 s33, s33, 0
	s_sub_i32 s0, s0, s67
	s_add_i32 s96, s95, s0
	s_cmp_lt_i32 s96, s33
	v_mov_b32_e32 v37, v156
	s_cselect_b64 s[44:45], -1, 0
	s_cmp_ge_i32 s96, s33
	s_waitcnt vmcnt(0) lgkmcnt(0)
	s_barrier
	s_cbranch_scc1 .LBB0_73
	s_mul_hi_i32 s0, s96, 0x60606061
	s_lshr_b32 s1, s0, 31
	s_ashr_i32 s0, s0, 11
	s_add_i32 s46, s0, s1
	s_mul_i32 s0, s46, 0x1540
	s_sub_i32 s15, s96, s0
	s_cmpk_gt_i32 s15, 0x57f
	s_mov_b64 s[0:1], -1
	s_cbranch_scc0 .LBB0_54
	s_cmpk_gt_u32 s15, 0x83f
	s_cbranch_scc0 .LBB0_51
	s_mov_b64 s[38:39], -1
	s_cmpk_gt_u32 s15, 0xbff
	s_cbranch_scc0 .LBB0_48
	s_cmpk_gt_u32 s15, 0xcff
	s_cbranch_scc0 .LBB0_45
	s_cmpk_gt_u32 s15, 0x127f
	s_cbranch_scc0 .LBB0_43
	s_add_i32 s0, s15, 0xed80
	s_and_b32 s1, s0, 0xffff
	s_mul_i32 s1, s1, 0xba2f
	s_lshr_b32 s3, s1, 21
	s_mul_i32 s1, s3, 44
	s_sub_i32 s0, s0, s1
	s_and_b32 s40, s0, 0xffff
	s_mul_i32 s0, s46, 0xb00
	s_ashr_i32 s1, s0, 31
	s_lshl_b64 s[0:1], s[0:1], 12
	v_readlane_b32 s56, v254, 1
	v_readlane_b32 s57, v254, 2
	v_readlane_b32 s62, v254, 7
	s_add_u32 s42, s56, s0
	v_readlane_b32 s58, v254, 3
	v_readlane_b32 s59, v254, 4
	v_readlane_b32 s60, v254, 5
	v_readlane_b32 s61, v254, 6
	v_readlane_b32 s63, v254, 8
	s_movk_i32 s62, 0x1000
	s_addc_u32 s43, s57, s1
	s_mov_b64 s[0:1], 0

; __device__ __forceinline__ void prep_load(const KP& p, int job, int tid, float (&v)[8], PrepMeta& m) {
;     ...
;     float x = sp[(size_t)k * ldn + c] * cs;
;     if (sc) x *= sc[k];
;     v[it] = ok ? x : 0.f;
.LBB0_113:
	s_or_b64 s[0:1], s[40:41], s[0:1]
	s_or_b64 vcc, s[0:1], s[42:43]
	v_readlane_b32 s66, v255, 40
	s_mov_b32 s94, 0x1c000
	v_writelane_b32 v108, s47, 4
	v_writelane_b32 v108, vcc_lo, 5
	v_writelane_b32 v108, vcc_hi, 6
	s_cmp_lg_u64 s[76:77], 0
	s_cselect_b32 s0, 1, 0
	v_writelane_b32 v108, s0, 7
	s_mov_b32 s99, 1
	s_mov_b32 s101, 1

; __device__ __forceinline__ void prep_load(const KP& p, int job, int tid, float (&v)[8], PrepMeta& m) {
;   int l = job / 5440, j = job % 5440;
;   int mat, nt, kt, K; size_t woff;
;   const float *s0, *s1, *sc; int ldn; float cs;
;   if (j < 1408) { mat = 0; nt = j / 16; kt = j % 16; K = DM; woff = W_GUA; s0 = p.in[7] + (size_t)l * DM * DFF; s1 = p.in[8] + (size_t)l * DM * DFF; sc = p.in[6] + l * DM; ldn = DFF; cs = 1.f; }
;   else if (j < 2112) { j -= 1408; mat = 1; nt = j / 44; kt = j % 44; K = DFF; woff = W_DA; s0 = s1 = p.in[9] + (size_t)l * DFF * DM; sc = nullptr; ldn = DM; cs = 0.5f; }
;   else if (j < 3072) { j -= 2112; mat = 2; nt = j / 16; kt = j % 16; K = DM; woff = W_IN; s0 = s1 = p.in[11] + (size_t)l * DM * 3592; sc = p.in[10] + l * DM; ldn = 3592; cs = 1.f; }
;   else if (j < 3328) { j -= 3072; mat = 3; nt = j / 16; kt = j % 16; K = DM; woff = W_OUT; s0 = s1 = p.in[20] + (size_t)l * DM * DM; sc = nullptr; ldn = DM; cs = 1.f; }
;   else if (j < 4736) { j -= 3328; mat = 0; nt = j / 16; kt = j % 16; K = DM; woff = W_GUB; s0 = p.in[22] + (size_t)l * DM * DFF; s1 = p.in[23] + (size_t)l * DM * DFF; sc = p.in[21] + l * DM; ldn = DFF; cs = 1.f; }
;   else { j -= 4736; mat = 1; nt = j / 44; kt = j % 44; K = DFF; woff = W_DB; s0 = s1 = p.in[24] + (size_t)l * DFF * DM; sc = nullptr; ldn = DM; cs = 0.5f; }
;     ...
;     float x = sp[(size_t)k * ldn + c] * cs;
;     if (sc) x *= sc[k];
;     v[it] = ok ? x : 0.f;
;   }
; }
; __device__ __forceinline__ void prep_tile_out(bfr* W, const float* tile, int tid, const float (&v)[8], const PrepMeta& m) {
; #pragma unroll
;   for (int it = 0; it < 8; ++it) { int e = tid + 512 * it; ((float*)tile)[(e >> 6) * 65 + (e & 63)] = v[it]; }
.LBB0_116:
	s_cmp_eq_u32 s98, 0
	s_cbranch_scc1 .LfinA_done
	s_cmp_eq_u32 s101, 0
	s_cbranch_scc1 .LfinA_w2
	s_waitcnt vmcnt(18)
	s_branch .LfinA_go
.LfinA_w2:
	s_waitcnt vmcnt(2)
.LfinA_go:
	v_readlane_b32 s0, v108, 0
	v_readlane_b32 vcc_lo, v108, 1
	v_readlane_b32 vcc_hi, v108, 2
	s_nop 3
	v_mul_f32_e32 v76, s0, v76
	v_mul_f32_e32 v77, s0, v77
	v_mul_f32_e32 v78, s0, v78
	v_mul_f32_e32 v79, s0, v79
	v_mul_f32_e32 v80, s0, v80
	v_mul_f32_e32 v81, s0, v81
	v_mul_f32_e32 v82, s0, v82
	v_mul_f32_e32 v83, s0, v83
	v_readlane_b32 s0, v108, 3
	s_nop 3
	s_cmp_eq_u32 s0, 0
	s_cbranch_scc1 .LfinA_nosc
	v_mul_f32_e32 v76, v76, v84
	v_mul_f32_e32 v77, v77, v85
	v_mul_f32_e32 v78, v78, v86
	v_mul_f32_e32 v79, v79, v87
	v_mul_f32_e32 v80, v80, v88
	v_mul_f32_e32 v81, v81, v89
	v_mul_f32_e32 v82, v82, v90
	v_mul_f32_e32 v83, v83, v91
.LfinA_nosc:
	v_cndmask_b32_e32 v2, 0, v76, vcc
	v_cndmask_b32_e32 v3, 0, v77, vcc
	v_cndmask_b32_e32 v4, 0, v78, vcc
	v_cndmask_b32_e32 v5, 0, v79, vcc
	v_cndmask_b32_e32 v6, 0, v80, vcc
	v_cndmask_b32_e32 v7, 0, v81, vcc
	v_cndmask_b32_e32 v8, 0, v82, vcc
	v_cndmask_b32_e32 v9, 0, v83, vcc
	s_mov_b32 s98, 0
.LfinA_done:
	s_mov_b32 s101, 0
	s_mul_i32 s0, s57, 0x4100
	s_add_i32 s63, s0, 0
	v_add3_u32 v41, s63, v17, v37
	ds_write_b32 v41, v2
	v_add3_u32 v41, s63, v19, v37
	ds_write_b32 v41, v3
	v_add3_u32 v41, s63, v21, v37
	ds_write_b32 v41, v4
	v_add3_u32 v41, s63, v23, v37
	ds_write_b32 v41, v5
	v_add3_u32 v41, s63, v25, v37
	s_add_i32 s59, s96, s56
	ds_write_b32 v41, v6
	v_add3_u32 v41, s63, v27, v37
	s_cmp_ge_i32 s59, s33
	ds_write_b32 v41, v7
	v_add3_u32 v41, s63, v29, v37
	s_cselect_b64 s[78:79], -1, 0
	ds_write_b32 v41, v8
	v_add3_u32 v41, s63, v31, v37
	s_and_b64 vcc, exec, s[78:79]
	s_mov_b32 s80, s46
	s_mov_b32 s62, s76
	ds_write_b32 v41, v9
	s_waitcnt lgkmcnt(0)
	s_barrier
	s_cbranch_vccnz .LBB0_153
	s_mul_hi_i32 s0, s59, 0x60606061
	s_lshr_b32 s1, s0, 31
	s_ashr_i32 s0, s0, 11
	s_add_i32 s80, s0, s1
	s_mul_i32 s0, s80, 0xffffeac0
	s_add_i32 s43, s59, s0
	s_cmpk_gt_i32 s43, 0x57f
	s_mov_b64 s[0:1], -1
	s_cbranch_scc0 .LBB0_134
	s_cmpk_gt_u32 s43, 0x83f
	s_cbranch_scc0 .LBB0_131
	s_mov_b64 s[40:41], -1
	s_cmpk_gt_u32 s43, 0xbff
	s_cbranch_scc0 .LBB0_128
	s_cmpk_gt_u32 s43, 0xcff
	s_cbranch_scc0 .LBB0_125
	s_cmpk_gt_u32 s43, 0x127f
	s_cbranch_scc0 .LBB0_123
	s_add_i32 s0, s43, 0xed80
	s_and_b32 s1, s0, 0xffff
	s_mul_i32 s1, s1, 0xba2f
	s_lshr_b32 s42, s1, 21
	s_mul_i32 s1, s42, 44
	s_sub_i32 s0, s0, s1
	s_and_b32 s62, s0, 0xffff
	s_mul_i32 s0, s80, 0xb00
	s_ashr_i32 s1, s0, 31
	s_mov_b64 s[44:45], s[68:69]
	v_readlane_b32 s64, v254, 1
	s_lshl_b64 s[0:1], s[0:1], 12
	v_readlane_b32 s68, v254, 5
	v_readlane_b32 s69, v254, 6
	v_readlane_b32 s65, v254, 2
	v_readlane_b32 s70, v254, 7
	v_readlane_b32 s71, v254, 8
	s_mov_b64 s[68:69], s[44:45]
	s_add_u32 s44, s64, s0
	v_readlane_b32 s66, v254, 3
	v_readlane_b32 s67, v254, 4
	s_mov_b64 s[70:71], 0x17ca9100
	s_addc_u32 s45, s65, s1
	s_mov_b64 s[0:1], 0

; __device__ __forceinline__ void prep_load(const KP& p, int job, int tid, float (&v)[8], PrepMeta& m) {
;     ...
;   for (int it = 0; it < 8; ++it) {
;     int e = tid + 512 * it, kk = e >> 6, nn = e & 63;
;     int k = k0 + kk, n = n0 + nn, c; bool ok = true; const float* sp = s0;
;     const int nl = n & 255, bj = nl >> 7, wc_ = (nl >> 5) & 3, ns = (nl >> 4) & 1, r = nl & 15;
;     if (mat == 0) { c = (n >> 8) * 128 + wc_ * 32 + (r >> 2) * 8 + bj * 4 + (r & 3); if (ns) sp = s1; }
;     else {
;       c = (n & ~255) + bj * 128 + wc_ * 32 + (r >> 2) * 8 + ns * 4 + (r & 3);
;       if (mat == 2) { if (c < 1536) c = c; else if (c < 3584) c = c + 8; else if (c < 3592) c = 1536 + (c - 3584); else { ok = false; c = 0; } }
;     }
;     float x = sp[(size_t)k * ldn + c] * cs;
.LBB0_136:
	s_lshl_b32 s61, s42, 6
	s_lshl_b32 s62, s62, 6
	s_bfe_u32 s43, s42, 0x10001
	v_or_b32_e32 v2, s61, v32
	s_cmp_lg_u64 s[84:85], 0
	v_bfe_u32 v2, v2, 5, 2
	s_cselect_b64 s[94:95], -1, 0
	s_and_b32 s0, s61, 0xffffff00
	s_lshl_b32 s1, s43, 7
	s_or_b32 s0, s1, s0
	v_lshlrev_b32_e32 v3, 5, v2
	v_or3_b32 v3, v3, s0, v33
	v_or_b32_e32 v4, v3, v34
	s_movk_i32 s0, 0x600
	s_cmpk_lt_u32 s61, 0xe00
	v_cmp_gt_i32_e32 vcc, s0, v4
	s_cselect_b64 s[0:1], -1, 0
	s_and_b32 s65, s42, 0x7fffffc
	s_movk_i32 s42, 0xe08
	v_or_b32_e32 v2, s65, v2
	v_mov_b32_e32 v6, s92
	v_mov_b32_e32 v7, s44
	s_lshl_b32 s66, s43, 2
	v_cmp_gt_u32_e64 s[42:43], s42, v3
	v_add_u32_e32 v3, 0xfffff800, v4
	v_lshlrev_b32_e32 v2, 5, v2
	v_cndmask_b32_e64 v8, v6, v7, s[38:39]
	v_mov_b32_e32 v6, s93
	v_mov_b32_e32 v9, s45
	s_or_b64 s[40:41], s[88:89], s[40:41]
	v_cndmask_b32_e64 v3, 0, v3, s[42:43]
	v_add_u32_e32 v5, 8, v4
	v_or3_b32 v2, v2, s66, v35
	v_cndmask_b32_e64 v41, v6, v9, s[38:39]
	v_add_u32_e32 v6, s62, v16
	s_or_b64 s[40:41], s[40:41], vcc
	v_cndmask_b32_e64 v2, v4, v2, s[88:89]
	v_cndmask_b32_e64 v3, v3, v5, s[0:1]
	v_cndmask_b32_e64 v4, v7, v8, s[88:89]
	v_ashrrev_i32_e32 v7, 31, v6
	v_cndmask_b32_e64 v2, v3, v2, s[40:41]
	v_cndmask_b32_e64 v5, v9, v41, s[88:89]
	v_mul_lo_u32 v3, s86, v7
	v_mul_lo_u32 v41, s87, v6
	v_mad_u64_u32 v[8:9], s[44:45], s86, v6, 0
	v_add3_u32 v9, v9, v3, v41
	v_ashrrev_i32_e32 v3, 31, v2
	v_lshl_add_u64 v[8:9], v[8:9], 2, v[4:5]
	v_lshl_add_u64 v[8:9], v[2:3], 2, v[8:9]
	global_load_dword v76, v[8:9], off
	v_mov_b32_e32 v110, v8
	v_mov_b32_e32 v111, v9
	s_cmp_eq_u64 s[84:85], 0
	s_cbranch_scc1 .LpdA_0
	v_lshl_add_u64 v[6:7], v[6:7], 2, s[84:85]
	global_load_dword v84, v[6:7], off
	s_branch .LBB0_138
.LpdA_0:
	global_load_dword v84, v[110:111], off
.LBB0_138:
	v_add_u32_e32 v6, s62, v18
	v_ashrrev_i32_e32 v7, 31, v6
	v_mul_lo_u32 v9, s86, v7
	v_mul_lo_u32 v41, s87, v6
	v_mad_u64_u32 v[42:43], s[44:45], s86, v6, 0
	v_add3_u32 v43, v43, v9, v41
	v_lshl_add_u64 v[42:43], v[42:43], 2, v[4:5]
	v_lshl_add_u64 v[42:43], v[2:3], 2, v[42:43]
	global_load_dword v77, v[42:43], off
	v_mov_b32_e32 v110, v42
	v_mov_b32_e32 v111, v43
	v_cndmask_b32_e64 v41, 0, 1, s[94:95]
	v_cmp_ne_u32_e64 s[44:45], 1, v41
	s_andn2_b64 vcc, exec, s[94:95]
	s_cbranch_vccnz .LpdA_1
	v_lshl_add_u64 v[6:7], v[6:7], 2, s[84:85]
	global_load_dword v85, v[6:7], off
	s_branch .LBB0_140
.LpdA_1:
	global_load_dword v85, v[110:111], off
.LBB0_140:
	v_add_u32_e32 v6, s62, v20
	v_ashrrev_i32_e32 v7, 31, v6
	v_mul_lo_u32 v41, s86, v7
	v_mul_lo_u32 v44, s87, v6
	v_mad_u64_u32 v[42:43], s[66:67], s86, v6, 0
	v_add3_u32 v43, v43, v41, v44
	v_lshl_add_u64 v[42:43], v[42:43], 2, v[4:5]
	v_lshl_add_u64 v[42:43], v[2:3], 2, v[42:43]
	global_load_dword v78, v[42:43], off
	v_mov_b32_e32 v110, v42
	v_mov_b32_e32 v111, v43
	s_and_b64 vcc, exec, s[44:45]
	s_cbranch_vccnz .LpdA_2
	v_lshl_add_u64 v[6:7], v[6:7], 2, s[84:85]
	global_load_dword v86, v[6:7], off
	s_branch .LBB0_142
.LpdA_2:
	global_load_dword v86, v[110:111], off
.LBB0_142:
	v_add_u32_e32 v6, s62, v22
	v_ashrrev_i32_e32 v7, 31, v6
	v_mul_lo_u32 v44, s86, v7
	v_mul_lo_u32 v45, s87, v6
	v_mad_u64_u32 v[42:43], s[66:67], s86, v6, 0
	v_add3_u32 v43, v43, v44, v45
	v_lshl_add_u64 v[42:43], v[42:43], 2, v[4:5]
	v_lshl_add_u64 v[42:43], v[2:3], 2, v[42:43]
	global_load_dword v79, v[42:43], off
	v_mov_b32_e32 v110, v42
	v_mov_b32_e32 v111, v43
	s_and_b64 vcc, exec, s[44:45]
	s_cbranch_vccnz .LpdA_3
	v_lshl_add_u64 v[6:7], v[6:7], 2, s[84:85]
	global_load_dword v87, v[6:7], off
	s_branch .LBB0_144
.LpdA_3:
	global_load_dword v87, v[110:111], off
; __device__ __forceinline__ unsigned pack2(float a, float b) { f32v2_t v = {a, b}; bf16v2_t r = __builtin_convertvector(v, bf16v2_t); return __builtin_bit_cast(unsigned, r); }
; __device__ __forceinline__ void prep_load(const KP& p, int job, int tid, float (&v)[8], PrepMeta& m) {
;     ...
;   for (int it = 0; it < 8; ++it) {
;     int e = tid + 512 * it, kk = e >> 6, nn = e & 63;
;     int k = k0 + kk, n = n0 + nn, c; bool ok = true; const float* sp = s0;
;     const int nl = n & 255, bj = nl >> 7, wc_ = (nl >> 5) & 3, ns = (nl >> 4) & 1, r = nl & 15;
;     if (mat == 0) { c = (n >> 8) * 128 + wc_ * 32 + (r >> 2) * 8 + bj * 4 + (r & 3); if (ns) sp = s1; }
;     else {
;       c = (n & ~255) + bj * 128 + wc_ * 32 + (r >> 2) * 8 + ns * 4 + (r & 3);
;       if (mat == 2) { if (c < 1536) c = c; else if (c < 3584) c = c + 8; else if (c < 3592) c = 1536 + (c - 3584); else { ok = false; c = 0; } }
;     }
;     float x = sp[(size_t)k * ldn + c] * cs;
;     if (sc) x *= sc[k];
;     v[it] = ok ? x : 0.f;
; __device__ void phase_prep(const KP& p, int job_lo, int job_hi, int first_blk) {
;     ...
;           int nn = tid >> 3, seg = tid & 7;
;           u32x4 v;
;           v[0] = pack2(tile[(seg * 8 + 0) * 65 + nn], tile[(seg * 8 + 1) * 65 + nn]);
;           v[1] = pack2(tile[(seg * 8 + 2) * 65 + nn], tile[(seg * 8 + 3) * 65 + nn]);
;           v[2] = pack2(tile[(seg * 8 + 4) * 65 + nn], tile[(seg * 8 + 5) * 65 + nn]);
;           v[3] = pack2(tile[(seg * 8 + 6) * 65 + nn], tile[(seg * 8 + 7) * 65 + nn]);
;           *(u32x4*)(W + (size_t)mc.l * W_LAYER + mc.woff + (size_t)(mc.n0 + nn) * mc.K + mc.k0 + seg * 8) = v;
.LBB0_144:
	v_add_u32_e32 v6, s62, v24
	v_ashrrev_i32_e32 v7, 31, v6
	v_mul_lo_u32 v43, s86, v7
	v_mul_lo_u32 v46, s87, v6
	v_mad_u64_u32 v[44:45], s[66:67], s86, v6, 0
	v_add3_u32 v45, v45, v43, v46
	v_lshl_add_u64 v[44:45], v[44:45], 2, v[4:5]
	v_lshl_add_u64 v[44:45], v[2:3], 2, v[44:45]
	global_load_dword v80, v[44:45], off
	v_mov_b32_e32 v110, v44
	v_mov_b32_e32 v111, v45
	s_and_b64 vcc, exec, s[44:45]
	s_cbranch_vccnz .LpdA_4
	v_lshl_add_u64 v[6:7], v[6:7], 2, s[84:85]
	global_load_dword v88, v[6:7], off
	s_branch .LBB0_146
.LpdA_4:
	global_load_dword v88, v[110:111], off
.LBB0_146:
	v_add_u32_e32 v6, s62, v26
	v_ashrrev_i32_e32 v7, 31, v6
	v_mul_lo_u32 v46, s86, v7
	v_mul_lo_u32 v47, s87, v6
	v_mad_u64_u32 v[44:45], s[66:67], s86, v6, 0
	v_add3_u32 v45, v45, v46, v47
	v_lshl_add_u64 v[44:45], v[44:45], 2, v[4:5]
	v_lshl_add_u64 v[44:45], v[2:3], 2, v[44:45]
	global_load_dword v81, v[44:45], off
	v_mov_b32_e32 v110, v44
	v_mov_b32_e32 v111, v45
	s_and_b64 vcc, exec, s[44:45]
	s_cbranch_vccnz .LpdA_5
	v_lshl_add_u64 v[6:7], v[6:7], 2, s[84:85]
	global_load_dword v89, v[6:7], off
	s_branch .LBB0_148
.LpdA_5:
	global_load_dword v89, v[110:111], off
.LBB0_148:
	v_add_u32_e32 v6, s62, v28
	v_ashrrev_i32_e32 v7, 31, v6
	v_mul_lo_u32 v45, s86, v7
	v_mul_lo_u32 v48, s87, v6
	v_mad_u64_u32 v[46:47], s[66:67], s86, v6, 0
	v_add3_u32 v47, v47, v45, v48
	v_lshl_add_u64 v[46:47], v[46:47], 2, v[4:5]
	v_lshl_add_u64 v[46:47], v[2:3], 2, v[46:47]
	global_load_dword v82, v[46:47], off
	v_mov_b32_e32 v110, v46
	v_mov_b32_e32 v111, v47
	s_and_b64 vcc, exec, s[44:45]
	s_cbranch_vccnz .LpdA_6
	v_lshl_add_u64 v[6:7], v[6:7], 2, s[84:85]
	global_load_dword v90, v[6:7], off
	s_branch .LBB0_150
.LpdA_6:
	global_load_dword v90, v[110:111], off
.LBB0_150:
	v_add_u32_e32 v6, s62, v30
	v_ashrrev_i32_e32 v7, 31, v6
	v_mul_lo_u32 v48, s86, v7
	v_mul_lo_u32 v49, s87, v6
	v_mad_u64_u32 v[46:47], s[66:67], s86, v6, 0
	v_add3_u32 v47, v47, v48, v49
	v_lshl_add_u64 v[4:5], v[46:47], 2, v[4:5]
	v_lshl_add_u64 v[2:3], v[2:3], 2, v[4:5]
	global_load_dword v83, v[2:3], off
	v_mov_b32_e32 v110, v2
	v_mov_b32_e32 v111, v3
	s_and_b64 vcc, exec, s[44:45]
	s_cbranch_vccnz .LpdA_7
	v_lshl_add_u64 v[2:3], v[6:7], 2, s[84:85]
	global_load_dword v91, v[2:3], off
	s_branch .LBB0_152
.LpdA_7:
	global_load_dword v91, v[110:111], off
.LBB0_152:
	s_or_b64 s[0:1], s[40:41], s[0:1]
	s_or_b64 vcc, s[0:1], s[42:43]
	v_readlane_b32 s66, v255, 40
	s_mov_b32 s94, 0x1c000
	v_writelane_b32 v108, s64, 0
	v_writelane_b32 v108, vcc_lo, 1
	v_writelane_b32 v108, vcc_hi, 2
	s_cmp_lg_u64 s[84:85], 0
	s_cselect_b32 s0, 1, 0
	v_writelane_b32 v108, s0, 3
	s_mov_b32 s98, 1
	s_mov_b32 s100, 1
.LBB0_153:
	v_lshlrev_b32_e32 v41, 2, v36
	v_add3_u32 v46, s63, v38, v41
	ds_read2_b32 v[42:43], v46 offset1:65
	ds_read2_b32 v[44:45], v46 offset0:130 offset1:195
	v_add_u32_e32 v46, 0x400, v46
	s_mul_i32 s1, s46, 0x2a80000
	s_mul_hi_i32 s0, s46, 0x2a80000
	s_waitcnt lgkmcnt(1)
	v_cvt_pk_bf16_f32 v42, v42, v43
	s_waitcnt lgkmcnt(0)
	v_cvt_pk_bf16_f32 v43, v44, v45
	ds_read2_b32 v[44:45], v46 offset0:4 offset1:69
	ds_read2_b32 v[46:47], v46 offset0:134 offset1:199
	s_add_u32 s40, s2, s1
	s_addc_u32 s41, s3, s0
	s_lshl_b64 s[0:1], s[52:53], 1
	s_waitcnt lgkmcnt(1)
	v_cvt_pk_bf16_f32 v44, v44, v45
	s_waitcnt lgkmcnt(0)
	v_cvt_pk_bf16_f32 v45, v46, v47
	s_add_u32 s0, s40, s0
	v_add_u32_e32 v46, s77, v36
	s_addc_u32 s1, s41, s1
	v_mad_i64_i32 v[46:47], s[40:41], v46, s47, 0
	v_lshl_add_u64 v[46:47], v[46:47], 1, s[0:1]
	s_ashr_i32 s77, s76, 31
	v_lshl_add_u64 v[46:47], s[76:77], 1, v[46:47]
	s_xor_b32 s0, s57, 1
	s_add_i32 s1, s72, s96
	v_lshl_add_u64 v[46:47], v[46:47], 0, v[0:1]
	s_cmp_ge_i32 s1, s33
	global_store_dwordx4 v[46:47], v[42:45], off
	s_cbranch_scc1 .LBB0_190
	s_cmp_eq_u32 s99, 0
	s_cbranch_scc1 .LfinB_done
	s_cmp_eq_u32 s100, 0
	s_cbranch_scc1 .LfinB_w2
	s_waitcnt vmcnt(18)
	s_branch .LfinB_go

; __device__ __forceinline__ void prep_load(const KP& p, int job, int tid, float (&v)[8], PrepMeta& m) {
;   int l = job / 5440, j = job % 5440;
;   int mat, nt, kt, K; size_t woff;
;   const float *s0, *s1, *sc; int ldn; float cs;
;   if (j < 1408) { mat = 0; nt = j / 16; kt = j % 16; K = DM; woff = W_GUA; s0 = p.in[7] + (size_t)l * DM * DFF; s1 = p.in[8] + (size_t)l * DM * DFF; sc = p.in[6] + l * DM; ldn = DFF; cs = 1.f; }
;   else if (j < 2112) { j -= 1408; mat = 1; nt = j / 44; kt = j % 44; K = DFF; woff = W_DA; s0 = s1 = p.in[9] + (size_t)l * DFF * DM; sc = nullptr; ldn = DM; cs = 0.5f; }
;   else if (j < 3072) { j -= 2112; mat = 2; nt = j / 16; kt = j % 16; K = DM; woff = W_IN; s0 = s1 = p.in[11] + (size_t)l * DM * 3592; sc = p.in[10] + l * DM; ldn = 3592; cs = 1.f; }
;   else if (j < 3328) { j -= 3072; mat = 3; nt = j / 16; kt = j % 16; K = DM; woff = W_OUT; s0 = s1 = p.in[20] + (size_t)l * DM * DM; sc = nullptr; ldn = DM; cs = 1.f; }
;   else if (j < 4736) { j -= 3328; mat = 0; nt = j / 16; kt = j % 16; K = DM; woff = W_GUB; s0 = p.in[22] + (size_t)l * DM * DFF; s1 = p.in[23] + (size_t)l * DM * DFF; sc = p.in[21] + l * DM; ldn = DFF; cs = 1.f; }
;   else { j -= 4736; mat = 1; nt = j / 44; kt = j % 44; K = DFF; woff = W_DB; s0 = s1 = p.in[24] + (size_t)l * DFF * DM; sc = nullptr; ldn = DM; cs = 0.5f; }
;     ...
;     float x = sp[(size_t)k * ldn + c] * cs;
;     if (sc) x *= sc[k];
;     v[it] = ok ? x : 0.f;
;   }
; }
; __device__ __forceinline__ void prep_tile_out(bfr* W, const float* tile, int tid, const float (&v)[8], const PrepMeta& m) {
; #pragma unroll
;   for (int it = 0; it < 8; ++it) { int e = tid + 512 * it; ((float*)tile)[(e >> 6) * 65 + (e & 63)] = v[it]; }
.LfinB_go:
	v_readlane_b32 s1, v108, 4
	v_readlane_b32 vcc_lo, v108, 5
	v_readlane_b32 vcc_hi, v108, 6
	s_nop 3
	v_mul_f32_e32 v92, s1, v92
	v_mul_f32_e32 v93, s1, v93
	v_mul_f32_e32 v94, s1, v94
	v_mul_f32_e32 v95, s1, v95
	v_mul_f32_e32 v96, s1, v96
	v_mul_f32_e32 v97, s1, v97
	v_mul_f32_e32 v98, s1, v98
	v_mul_f32_e32 v99, s1, v99
	v_readlane_b32 s1, v108, 7
	s_nop 3
	s_cmp_eq_u32 s1, 0
	s_cbranch_scc1 .LfinB_nosc
	v_mul_f32_e32 v92, v92, v100
	v_mul_f32_e32 v93, v93, v101
	v_mul_f32_e32 v94, v94, v102
	v_mul_f32_e32 v95, v95, v103
	v_mul_f32_e32 v96, v96, v104
	v_mul_f32_e32 v97, v97, v105
	v_mul_f32_e32 v98, v98, v106
	v_mul_f32_e32 v99, v99, v107
.LfinB_nosc:
	v_cndmask_b32_e32 v39, 0, v92, vcc
	v_cndmask_b32_e32 v15, 0, v93, vcc
	v_cndmask_b32_e32 v14, 0, v94, vcc
	v_cndmask_b32_e32 v13, 0, v95, vcc
	v_cndmask_b32_e32 v12, 0, v96, vcc
	v_cndmask_b32_e32 v11, 0, v97, vcc
	v_cndmask_b32_e32 v10, 0, v98, vcc
	v_cndmask_b32_e32 v40, 0, v99, vcc
	s_mov_b32 s99, 0
.LfinB_done:
	s_mov_b32 s100, 0
	s_mulk_i32 s0, 0x4100
	s_add_i32 s63, s0, 0
	v_add3_u32 v42, s63, v17, v37
	ds_write_b32 v42, v39
	v_add3_u32 v42, s63, v19, v37
	ds_write_b32 v42, v15
	v_add3_u32 v42, s63, v21, v37
	ds_write_b32 v42, v14
	v_add3_u32 v42, s63, v23, v37
	ds_write_b32 v42, v13
	v_add3_u32 v42, s63, v25, v37
	ds_write_b32 v42, v12
	v_add3_u32 v42, s63, v27, v37
	ds_write_b32 v42, v11
	v_add3_u32 v42, s63, v29, v37
	s_add_i32 s0, s58, s96
	ds_write_b32 v42, v10
	v_add3_u32 v42, s63, v31, v37
	s_cmp_ge_i32 s0, s33
	s_mov_b32 s46, s36
	s_mov_b64 s[52:53], s[50:51]
	s_mov_b32 s64, s74
	s_mov_b32 s65, s37
	s_mov_b32 s14, s75
	ds_write_b32 v42, v40
	s_waitcnt lgkmcnt(0)
	s_barrier
	s_cbranch_scc1 .LBB0_114
	s_mul_hi_i32 s1, s0, 0x60606061
	s_lshr_b32 s14, s1, 31
	s_ashr_i32 s1, s1, 11
	s_add_i32 s46, s1, s14
	s_mul_i32 s1, s46, 0x1540
	s_sub_i32 s43, s0, s1
	s_cmpk_lt_i32 s43, 0x580
	s_mov_b64 s[0:1], -1
	s_cbranch_scc1 .LBB0_172
	s_cmpk_lt_u32 s43, 0x840
	s_cbranch_scc1 .LBB0_169
	s_mov_b64 s[40:41], -1
	s_cmpk_lt_u32 s43, 0xc00
	s_cbranch_scc1 .LBB0_166
	s_cmpk_lt_u32 s43, 0xd00
	s_cbranch_scc1 .LBB0_163
	s_cmpk_lt_u32 s43, 0x1280
	s_cbranch_scc1 .LBB0_161
	s_add_i32 s0, s43, 0xed80
	s_and_b32 s1, s0, 0xffff
	s_mul_i32 s1, s1, 0xba2f
	s_lshr_b32 s42, s1, 21
	s_mul_i32 s1, s42, 44
	s_sub_i32 s0, s0, s1
	s_and_b32 s64, s0, 0xffff
	s_mul_i32 s0, s46, 0xb00
	s_ashr_i32 s1, s0, 31
	s_lshl_b64 s[0:1], s[0:1], 12
	v_readlane_b32 s84, v254, 1
	v_readlane_b32 s85, v254, 2
	v_readlane_b32 s90, v254, 7
	v_readlane_b32 s91, v254, 8
	s_add_u32 s44, s84, s0
	s_mov_b64 s[90:91], 0x19129100
	s_mov_b64 s[70:71], 0x17ca9100
	s_addc_u32 s45, s85, s1
	s_mov_b64 s[0:1], 0
	v_readlane_b32 s86, v254, 3
	v_readlane_b32 s87, v254, 4
	v_readlane_b32 s88, v254, 5
	v_readlane_b32 s89, v254, 6

; __device__ __forceinline__ void prep_load(const KP& p, int job, int tid, float (&v)[8], PrepMeta& m) {
;     ...
;   for (int it = 0; it < 8; ++it) {
;     int e = tid + 512 * it, kk = e >> 6, nn = e & 63;
;     int k = k0 + kk, n = n0 + nn, c; bool ok = true; const float* sp = s0;
;     const int nl = n & 255, bj = nl >> 7, wc_ = (nl >> 5) & 3, ns = (nl >> 4) & 1, r = nl & 15;
;     if (mat == 0) { c = (n >> 8) * 128 + wc_ * 32 + (r >> 2) * 8 + bj * 4 + (r & 3); if (ns) sp = s1; }
;     else {
;       c = (n & ~255) + bj * 128 + wc_ * 32 + (r >> 2) * 8 + ns * 4 + (r & 3);
;       if (mat == 2) { if (c < 1536) c = c; else if (c < 3584) c = c + 8; else if (c < 3592) c = 1536 + (c - 3584); else { ok = false; c = 0; } }
;     }
;     float x = sp[(size_t)k * ldn + c] * cs;
.LBB0_174:
	s_lshl_b32 s65, s42, 6
	s_lshl_b32 s64, s64, 6
	s_bfe_u32 s43, s42, 0x10001
	v_or_b32_e32 v10, s65, v32
	s_cmp_lg_u64 s[76:77], 0
	v_bfe_u32 v10, v10, 5, 2
	s_cselect_b64 s[92:93], -1, 0
	s_and_b32 s0, s65, 0xffffff00
	s_lshl_b32 s1, s43, 7
	s_or_b32 s0, s1, s0
	v_lshlrev_b32_e32 v11, 5, v10
	v_or3_b32 v11, v11, s0, v33
	v_or_b32_e32 v12, v11, v34
	s_movk_i32 s0, 0x600
	s_cmpk_lt_u32 s65, 0xe00
	v_cmp_gt_i32_e32 vcc, s0, v12
	s_cselect_b64 s[0:1], -1, 0
	s_and_b32 s66, s42, 0x7fffffc
	s_movk_i32 s42, 0xe08
	v_or_b32_e32 v10, s66, v10
	v_mov_b32_e32 v14, s88
	v_mov_b32_e32 v15, s44
	s_lshl_b32 s67, s43, 2
	v_cmp_gt_u32_e64 s[42:43], s42, v11
	v_add_u32_e32 v11, 0xfffff800, v12
	v_lshlrev_b32_e32 v10, 5, v10
	v_cndmask_b32_e64 v39, v14, v15, s[38:39]
	v_mov_b32_e32 v14, s89
	v_mov_b32_e32 v40, s45
	s_or_b64 s[40:41], s[86:87], s[40:41]
	v_cndmask_b32_e64 v11, 0, v11, s[42:43]
	v_add_u32_e32 v13, 8, v12
	v_or3_b32 v10, v10, s67, v35
	v_cndmask_b32_e64 v42, v14, v40, s[38:39]
	v_add_u32_e32 v14, s64, v16
	s_or_b64 s[40:41], s[40:41], vcc
	v_cndmask_b32_e64 v10, v12, v10, s[86:87]
	v_cndmask_b32_e64 v11, v11, v13, s[0:1]
	v_cndmask_b32_e64 v12, v15, v39, s[86:87]
	v_ashrrev_i32_e32 v15, 31, v14
	v_cndmask_b32_e64 v10, v11, v10, s[40:41]
	v_cndmask_b32_e64 v13, v40, v42, s[86:87]
	v_mul_lo_u32 v11, s84, v15
	v_mul_lo_u32 v39, s85, v14
	v_mad_u64_u32 v[42:43], s[44:45], s84, v14, 0
	v_add3_u32 v43, v43, v11, v39
	v_ashrrev_i32_e32 v11, 31, v10
	v_lshl_add_u64 v[42:43], v[42:43], 2, v[12:13]
	v_lshl_add_u64 v[42:43], v[10:11], 2, v[42:43]
	global_load_dword v92, v[42:43], off
	v_mov_b32_e32 v110, v42
	v_mov_b32_e32 v111, v43
	s_cmp_eq_u64 s[76:77], 0
	s_cbranch_scc1 .LpdB_0
	v_lshl_add_u64 v[14:15], v[14:15], 2, s[76:77]
	global_load_dword v100, v[14:15], off
	s_branch .LBB0_176
.LpdB_0:
	global_load_dword v100, v[110:111], off
.LBB0_176:
	v_add_u32_e32 v14, s64, v18
	v_ashrrev_i32_e32 v15, 31, v14
	v_mul_lo_u32 v40, s84, v15
	v_mul_lo_u32 v44, s85, v14
	v_mad_u64_u32 v[42:43], s[44:45], s84, v14, 0
	v_add3_u32 v43, v43, v40, v44
	v_lshl_add_u64 v[42:43], v[42:43], 2, v[12:13]
	v_lshl_add_u64 v[42:43], v[10:11], 2, v[42:43]
	global_load_dword v93, v[42:43], off
	v_mov_b32_e32 v110, v42
	v_mov_b32_e32 v111, v43
	v_cndmask_b32_e64 v42, 0, 1, s[92:93]
	v_cmp_ne_u32_e64 s[44:45], 1, v42
	s_andn2_b64 vcc, exec, s[92:93]
	s_cbranch_vccnz .LpdB_1
	v_lshl_add_u64 v[14:15], v[14:15], 2, s[76:77]
	global_load_dword v101, v[14:15], off
	s_branch .LBB0_178
.LpdB_1:
	global_load_dword v101, v[110:111], off
.LBB0_178:
	v_add_u32_e32 v14, s64, v20
	v_ashrrev_i32_e32 v15, 31, v14
	v_mul_lo_u32 v44, s84, v15
	v_mul_lo_u32 v45, s85, v14
	v_mad_u64_u32 v[42:43], s[66:67], s84, v14, 0
	v_add3_u32 v43, v43, v44, v45
	v_lshl_add_u64 v[42:43], v[42:43], 2, v[12:13]
	v_lshl_add_u64 v[42:43], v[10:11], 2, v[42:43]
	global_load_dword v94, v[42:43], off
	v_mov_b32_e32 v110, v42
	v_mov_b32_e32 v111, v43
	s_and_b64 vcc, exec, s[44:45]
	s_cbranch_vccnz .LpdB_2
	v_lshl_add_u64 v[14:15], v[14:15], 2, s[76:77]
	global_load_dword v102, v[14:15], off
	s_branch .LBB0_180
.LpdB_2:
	global_load_dword v102, v[110:111], off
.LBB0_180:
	v_add_u32_e32 v14, s64, v22
	v_ashrrev_i32_e32 v15, 31, v14
	v_mul_lo_u32 v43, s84, v15
	v_mul_lo_u32 v46, s85, v14
	v_mad_u64_u32 v[44:45], s[66:67], s84, v14, 0
	v_add3_u32 v45, v45, v43, v46
	v_lshl_add_u64 v[44:45], v[44:45], 2, v[12:13]
	v_lshl_add_u64 v[44:45], v[10:11], 2, v[44:45]
	global_load_dword v95, v[44:45], off
	v_mov_b32_e32 v110, v44
	v_mov_b32_e32 v111, v45
	s_and_b64 vcc, exec, s[44:45]
	s_cbranch_vccnz .LpdB_3
	v_lshl_add_u64 v[14:15], v[14:15], 2, s[76:77]
	global_load_dword v103, v[14:15], off
	s_branch .LBB0_182
.LpdB_3:
	global_load_dword v103, v[110:111], off
.LBB0_182:
	v_add_u32_e32 v14, s64, v24
	v_ashrrev_i32_e32 v15, 31, v14
	v_mul_lo_u32 v46, s84, v15
	v_mul_lo_u32 v47, s85, v14
	v_mad_u64_u32 v[44:45], s[66:67], s84, v14, 0
	v_add3_u32 v45, v45, v46, v47
	v_lshl_add_u64 v[44:45], v[44:45], 2, v[12:13]
	v_lshl_add_u64 v[44:45], v[10:11], 2, v[44:45]
	global_load_dword v96, v[44:45], off
	v_mov_b32_e32 v110, v44
	v_mov_b32_e32 v111, v45
	s_and_b64 vcc, exec, s[44:45]
	s_cbranch_vccnz .LpdB_4
	v_lshl_add_u64 v[14:15], v[14:15], 2, s[76:77]
	global_load_dword v104, v[14:15], off
	s_branch .LBB0_184
.LpdB_4:
	global_load_dword v104, v[110:111], off
.LBB0_184:
	v_add_u32_e32 v14, s64, v26
	v_ashrrev_i32_e32 v15, 31, v14
	v_mul_lo_u32 v45, s84, v15
	v_mul_lo_u32 v48, s85, v14
	v_mad_u64_u32 v[46:47], s[66:67], s84, v14, 0
	v_add3_u32 v47, v47, v45, v48
	v_lshl_add_u64 v[46:47], v[46:47], 2, v[12:13]
	v_lshl_add_u64 v[46:47], v[10:11], 2, v[46:47]
	global_load_dword v97, v[46:47], off
	v_mov_b32_e32 v110, v46
	v_mov_b32_e32 v111, v47
	s_and_b64 vcc, exec, s[44:45]
	s_cbranch_vccnz .LpdB_5
	v_lshl_add_u64 v[14:15], v[14:15], 2, s[76:77]
	global_load_dword v105, v[14:15], off
	s_branch .LBB0_186
.LpdB_5:
	global_load_dword v105, v[110:111], off
.LBB0_186:
	v_add_u32_e32 v14, s64, v28
	v_ashrrev_i32_e32 v15, 31, v14
	v_mul_lo_u32 v48, s84, v15
	v_mul_lo_u32 v49, s85, v14
	v_mad_u64_u32 v[46:47], s[66:67], s84, v14, 0
	v_add3_u32 v47, v47, v48, v49
	v_lshl_add_u64 v[46:47], v[46:47], 2, v[12:13]
	v_lshl_add_u64 v[46:47], v[10:11], 2, v[46:47]
	global_load_dword v98, v[46:47], off
	v_mov_b32_e32 v110, v46
	v_mov_b32_e32 v111, v47
	s_and_b64 vcc, exec, s[44:45]
	s_cbranch_vccnz .LpdB_6
	v_lshl_add_u64 v[14:15], v[14:15], 2, s[76:77]
	global_load_dword v106, v[14:15], off
	s_branch .LBB0_188
.LpdB_6:
	global_load_dword v106, v[110:111], off
.LBB0_188:
	v_add_u32_e32 v14, s64, v30
	v_ashrrev_i32_e32 v15, 31, v14
	v_mul_lo_u32 v47, s84, v15
	v_mul_lo_u32 v50, s85, v14
	v_mad_u64_u32 v[48:49], s[66:67], s84, v14, 0
	v_add3_u32 v49, v49, v47, v50
	v_lshl_add_u64 v[12:13], v[48:49], 2, v[12:13]
	v_lshl_add_u64 v[10:11], v[10:11], 2, v[12:13]
	global_load_dword v99, v[10:11], off
	v_mov_b32_e32 v110, v10
	v_mov_b32_e32 v111, v11
	s_and_b64 vcc, exec, s[44:45]
	s_cbranch_vccnz .LpdB_7
	v_lshl_add_u64 v[10:11], v[14:15], 2, s[76:77]
	global_load_dword v107, v[10:11], off
	s_branch .LBB0_113
.LpdB_7:
	global_load_dword v107, v[110:111], off
	s_branch .LBB0_113
